# DV2 per-map epilogue: quad transpose then one dwordx4 scratch store per q row instead of four dword stores (64 -> 16 stores per wave), on top of the widened finishing-loop og stores
# baseline (speedup 1.0000x reference)
; __device__ __forceinline__ int crow(int r,int hi){return (r&3)+8*(r>>2)+4*hi;}
;     ...
;   if(hi==0)wsf[32+r32]=l_reg;asm volatile("s_waitcnt lgkmcnt(0)":::"memory");
;   float rli[16];
;   #pragma unroll
;   for(int r=0;r<16;++r)rli[r]=__builtin_amdgcn_rcpf(wsf[32+crow(r,hi)]);
;   if constexpr(DV2){ float*Orw=Oraw+(long)wid*QBLK*128;
;     #pragma unroll
;     for(int r=0;r<16;++r){const int orow=crow(r,hi);
;       #pragma unroll
;       for(int d0=0;d0<4;++d0) Orw[orow*128+d0*32+r32]=o[d0][r]*rli[r];}
.LBB0_257:
	s_or_b64 exec, exec, s[6:7]
	s_waitcnt lgkmcnt(0)
	ds_read_b128 v[4:7], v2 offset:49280
	ds_read_b128 v[8:11], v2 offset:49312
	s_lshl_b32 s82, s42, 15
	s_lshl_b64 s[6:7], s[82:83], 2
	v_readlane_b32 s8, v254, 44
	s_waitcnt lgkmcnt(1)
	v_rcp_f32_e32 v12, v4
	v_rcp_f32_e32 v13, v5
	v_rcp_f32_e32 v14, v6
	v_rcp_f32_e32 v15, v7
	ds_read_b128 v[4:7], v2 offset:49344
	v_readlane_b32 s9, v254, 45
	s_add_u32 s8, s8, s6
	s_addc_u32 s9, s9, s7
	s_lshl_b64 s[6:7], s[30:31], 14
	s_add_u32 s6, s8, s6
	v_lshlrev_b32_e32 v0, 2, v211
	s_waitcnt lgkmcnt(1)
	v_rcp_f32_e32 v82, v8
	v_rcp_f32_e32 v83, v9
	v_rcp_f32_e32 v84, v10
	v_rcp_f32_e32 v85, v11
	ds_read_b128 v[8:11], v2 offset:49376
	s_waitcnt lgkmcnt(1)
	v_rcp_f32_e32 v86, v4
	s_addc_u32 s7, s9, s7
	s_mov_b32 s16, 0x55555555
	s_mov_b32 s17, 0x55555555
	s_mov_b32 s18, 0xaaaaaaaa
	s_mov_b32 s19, 0xaaaaaaaa
	s_mov_b32 s20, 0x33333333
	s_mov_b32 s21, 0x33333333
	s_mov_b32 s22, 0xcccccccc
	s_mov_b32 s23, 0xcccccccc
	v_mul_f32_e32 v92, v66, v12
	v_lshl_or_b32 v0, v242, 11, v0
	v_and_b32_e32 v100, 3, v234
	v_mul_u32_u24_e32 v100, 0x7c, v100
	v_add_u32_e32 v0, v0, v100
	v_mul_f32_e32 v93, v50, v12
	v_mul_f32_e32 v94, v34, v12
	v_mul_f32_e32 v95, v18, v12
	s_mov_b64 s[32:33], vcc
	s_nop 0
	s_mov_b64 vcc, s[16:17]
	v_cndmask_b32_dpp v96, v93, v92, vcc quad_perm:[1,0,3,2] row_mask:0xf bank_mask:0xf
	v_cndmask_b32_dpp v97, v95, v94, vcc quad_perm:[1,0,3,2] row_mask:0xf bank_mask:0xf
	s_mov_b64 vcc, s[18:19]
	v_cndmask_b32_dpp v98, v92, v93, vcc quad_perm:[1,0,3,2] row_mask:0xf bank_mask:0xf
	v_cndmask_b32_dpp v95, v94, v95, vcc quad_perm:[1,0,3,2] row_mask:0xf bank_mask:0xf
	s_mov_b64 vcc, s[20:21]
	v_cndmask_b32_dpp v92, v97, v96, vcc quad_perm:[2,3,0,1] row_mask:0xf bank_mask:0xf
	v_cndmask_b32_dpp v93, v95, v98, vcc quad_perm:[2,3,0,1] row_mask:0xf bank_mask:0xf
	s_mov_b64 vcc, s[22:23]
	v_cndmask_b32_dpp v94, v96, v97, vcc quad_perm:[2,3,0,1] row_mask:0xf bank_mask:0xf
	v_cndmask_b32_dpp v95, v98, v95, vcc quad_perm:[2,3,0,1] row_mask:0xf bank_mask:0xf
	s_mov_b64 vcc, s[32:33]
	global_store_dwordx4 v0, v[92:95], s[6:7]
	v_mul_f32_e32 v104, v67, v13
	v_mul_f32_e32 v105, v51, v13
	v_mul_f32_e32 v106, v35, v13
	v_mul_f32_e32 v107, v19, v13
	s_mov_b64 s[32:33], vcc
	s_nop 0
	s_mov_b64 vcc, s[16:17]
	v_cndmask_b32_dpp v96, v105, v104, vcc quad_perm:[1,0,3,2] row_mask:0xf bank_mask:0xf
	v_cndmask_b32_dpp v97, v107, v106, vcc quad_perm:[1,0,3,2] row_mask:0xf bank_mask:0xf
	s_mov_b64 vcc, s[18:19]
	v_cndmask_b32_dpp v98, v104, v105, vcc quad_perm:[1,0,3,2] row_mask:0xf bank_mask:0xf
	v_cndmask_b32_dpp v107, v106, v107, vcc quad_perm:[1,0,3,2] row_mask:0xf bank_mask:0xf
	s_mov_b64 vcc, s[20:21]
	v_cndmask_b32_dpp v104, v97, v96, vcc quad_perm:[2,3,0,1] row_mask:0xf bank_mask:0xf
	v_cndmask_b32_dpp v105, v107, v98, vcc quad_perm:[2,3,0,1] row_mask:0xf bank_mask:0xf
	s_mov_b64 vcc, s[22:23]
	v_cndmask_b32_dpp v106, v96, v97, vcc quad_perm:[2,3,0,1] row_mask:0xf bank_mask:0xf
	v_cndmask_b32_dpp v107, v98, v107, vcc quad_perm:[2,3,0,1] row_mask:0xf bank_mask:0xf
	s_mov_b64 vcc, s[32:33]
	global_store_dwordx4 v0, v[104:107], s[6:7] offset:512
	v_mul_f32_e32 v92, v68, v14
	v_mul_f32_e32 v93, v52, v14
	v_mul_f32_e32 v94, v36, v14
	v_mul_f32_e32 v95, v20, v14
	s_mov_b64 s[32:33], vcc
	s_nop 0
	s_mov_b64 vcc, s[16:17]
	v_cndmask_b32_dpp v96, v93, v92, vcc quad_perm:[1,0,3,2] row_mask:0xf bank_mask:0xf
	v_cndmask_b32_dpp v97, v95, v94, vcc quad_perm:[1,0,3,2] row_mask:0xf bank_mask:0xf
	s_mov_b64 vcc, s[18:19]
	v_cndmask_b32_dpp v98, v92, v93, vcc quad_perm:[1,0,3,2] row_mask:0xf bank_mask:0xf
	v_cndmask_b32_dpp v95, v94, v95, vcc quad_perm:[1,0,3,2] row_mask:0xf bank_mask:0xf
	s_mov_b64 vcc, s[20:21]
	v_cndmask_b32_dpp v92, v97, v96, vcc quad_perm:[2,3,0,1] row_mask:0xf bank_mask:0xf
	v_cndmask_b32_dpp v93, v95, v98, vcc quad_perm:[2,3,0,1] row_mask:0xf bank_mask:0xf
	s_mov_b64 vcc, s[22:23]
	v_cndmask_b32_dpp v94, v96, v97, vcc quad_perm:[2,3,0,1] row_mask:0xf bank_mask:0xf
	v_cndmask_b32_dpp v95, v98, v95, vcc quad_perm:[2,3,0,1] row_mask:0xf bank_mask:0xf
	s_mov_b64 vcc, s[32:33]
	global_store_dwordx4 v0, v[92:95], s[6:7] offset:1024
	v_mul_f32_e32 v104, v69, v15
	v_mul_f32_e32 v105, v53, v15
	v_mul_f32_e32 v106, v37, v15
	v_lshl_add_u64 v[2:3], s[6:7], 0, v[0:1]
	v_mul_f32_e32 v107, v21, v15
	s_mov_b64 s[32:33], vcc
	s_nop 0
	s_mov_b64 vcc, s[16:17]
	v_cndmask_b32_dpp v96, v105, v104, vcc quad_perm:[1,0,3,2] row_mask:0xf bank_mask:0xf
	v_cndmask_b32_dpp v97, v107, v106, vcc quad_perm:[1,0,3,2] row_mask:0xf bank_mask:0xf
	s_mov_b64 vcc, s[18:19]
	v_cndmask_b32_dpp v98, v104, v105, vcc quad_perm:[1,0,3,2] row_mask:0xf bank_mask:0xf
	v_cndmask_b32_dpp v107, v106, v107, vcc quad_perm:[1,0,3,2] row_mask:0xf bank_mask:0xf
	s_mov_b64 vcc, s[20:21]
	v_cndmask_b32_dpp v104, v97, v96, vcc quad_perm:[2,3,0,1] row_mask:0xf bank_mask:0xf
	v_cndmask_b32_dpp v105, v107, v98, vcc quad_perm:[2,3,0,1] row_mask:0xf bank_mask:0xf
	s_mov_b64 vcc, s[22:23]
	v_cndmask_b32_dpp v106, v96, v97, vcc quad_perm:[2,3,0,1] row_mask:0xf bank_mask:0xf
	v_cndmask_b32_dpp v107, v98, v107, vcc quad_perm:[2,3,0,1] row_mask:0xf bank_mask:0xf
	s_mov_b64 vcc, s[32:33]
	global_store_dwordx4 v0, v[104:107], s[6:7] offset:1536
	v_add_co_u32_e32 v4, vcc, s60, v2
	v_rcp_f32_e32 v87, v5
	s_nop 0
	v_addc_co_u32_e32 v5, vcc, 0, v3, vcc
	s_movk_i32 s6, 0x2000
	v_rcp_f32_e32 v88, v6
	v_add_co_u32_e32 v6, vcc, s6, v2
	v_rcp_f32_e32 v89, v7
	v_mul_f32_e32 v92, v70, v82
	v_addc_co_u32_e32 v7, vcc, 0, v3, vcc
	v_mul_f32_e32 v93, v54, v82
	v_mul_f32_e32 v94, v38, v82
	v_mul_f32_e32 v95, v22, v82
	s_mov_b64 s[32:33], vcc
	s_nop 0
	s_mov_b64 vcc, s[16:17]
; __device__ __forceinline__ int crow(int r,int hi){return (r&3)+8*(r>>2)+4*hi;}
;     ...
;   if constexpr(DV2){ float*Orw=Oraw+(long)wid*QBLK*128;
;     #pragma unroll
;     for(int r=0;r<16;++r){const int orow=crow(r,hi);
;       #pragma unroll
;       for(int d0=0;d0<4;++d0) Orw[orow*128+d0*32+r32]=o[d0][r]*rli[r];}
	v_cndmask_b32_dpp v96, v93, v92, vcc quad_perm:[1,0,3,2] row_mask:0xf bank_mask:0xf
	v_cndmask_b32_dpp v97, v95, v94, vcc quad_perm:[1,0,3,2] row_mask:0xf bank_mask:0xf
	s_mov_b64 vcc, s[18:19]
	v_cndmask_b32_dpp v98, v92, v93, vcc quad_perm:[1,0,3,2] row_mask:0xf bank_mask:0xf
	v_cndmask_b32_dpp v95, v94, v95, vcc quad_perm:[1,0,3,2] row_mask:0xf bank_mask:0xf
	s_mov_b64 vcc, s[20:21]
	v_cndmask_b32_dpp v92, v97, v96, vcc quad_perm:[2,3,0,1] row_mask:0xf bank_mask:0xf
	v_cndmask_b32_dpp v93, v95, v98, vcc quad_perm:[2,3,0,1] row_mask:0xf bank_mask:0xf
	s_mov_b64 vcc, s[22:23]
	v_cndmask_b32_dpp v94, v96, v97, vcc quad_perm:[2,3,0,1] row_mask:0xf bank_mask:0xf
	v_cndmask_b32_dpp v95, v98, v95, vcc quad_perm:[2,3,0,1] row_mask:0xf bank_mask:0xf
	s_mov_b64 vcc, s[32:33]
	global_store_dwordx4 v[4:5], v[92:95], off
	v_mul_f32_e32 v104, v71, v83
	v_mul_f32_e32 v105, v55, v83
	v_mul_f32_e32 v106, v39, v83
	v_mul_f32_e32 v107, v23, v83
	s_mov_b64 s[32:33], vcc
	s_nop 0
	s_mov_b64 vcc, s[16:17]
	v_cndmask_b32_dpp v96, v105, v104, vcc quad_perm:[1,0,3,2] row_mask:0xf bank_mask:0xf
	v_cndmask_b32_dpp v97, v107, v106, vcc quad_perm:[1,0,3,2] row_mask:0xf bank_mask:0xf
	s_mov_b64 vcc, s[18:19]
	v_cndmask_b32_dpp v98, v104, v105, vcc quad_perm:[1,0,3,2] row_mask:0xf bank_mask:0xf
	v_cndmask_b32_dpp v107, v106, v107, vcc quad_perm:[1,0,3,2] row_mask:0xf bank_mask:0xf
	s_mov_b64 vcc, s[20:21]
	v_cndmask_b32_dpp v104, v97, v96, vcc quad_perm:[2,3,0,1] row_mask:0xf bank_mask:0xf
	v_cndmask_b32_dpp v105, v107, v98, vcc quad_perm:[2,3,0,1] row_mask:0xf bank_mask:0xf
	s_mov_b64 vcc, s[22:23]
	v_cndmask_b32_dpp v106, v96, v97, vcc quad_perm:[2,3,0,1] row_mask:0xf bank_mask:0xf
	v_cndmask_b32_dpp v107, v98, v107, vcc quad_perm:[2,3,0,1] row_mask:0xf bank_mask:0xf
	s_mov_b64 vcc, s[32:33]
	global_store_dwordx4 v[4:5], v[104:107], off offset:512
	v_mul_f32_e32 v92, v72, v84
	v_mul_f32_e32 v93, v56, v84
	v_mul_f32_e32 v94, v40, v84
	v_mul_f32_e32 v95, v24, v84
	s_mov_b64 s[32:33], vcc
	s_nop 0
	s_mov_b64 vcc, s[16:17]
	v_cndmask_b32_dpp v96, v93, v92, vcc quad_perm:[1,0,3,2] row_mask:0xf bank_mask:0xf
	v_cndmask_b32_dpp v97, v95, v94, vcc quad_perm:[1,0,3,2] row_mask:0xf bank_mask:0xf
	s_mov_b64 vcc, s[18:19]
	v_cndmask_b32_dpp v98, v92, v93, vcc quad_perm:[1,0,3,2] row_mask:0xf bank_mask:0xf
	v_cndmask_b32_dpp v95, v94, v95, vcc quad_perm:[1,0,3,2] row_mask:0xf bank_mask:0xf
	s_mov_b64 vcc, s[20:21]
	v_cndmask_b32_dpp v92, v97, v96, vcc quad_perm:[2,3,0,1] row_mask:0xf bank_mask:0xf
	v_cndmask_b32_dpp v93, v95, v98, vcc quad_perm:[2,3,0,1] row_mask:0xf bank_mask:0xf
	s_mov_b64 vcc, s[22:23]
	v_cndmask_b32_dpp v94, v96, v97, vcc quad_perm:[2,3,0,1] row_mask:0xf bank_mask:0xf
	v_cndmask_b32_dpp v95, v98, v95, vcc quad_perm:[2,3,0,1] row_mask:0xf bank_mask:0xf
	s_mov_b64 vcc, s[32:33]
	global_store_dwordx4 v[4:5], v[92:95], off offset:1024
	v_mul_f32_e32 v104, v73, v85
	v_mul_f32_e32 v105, v57, v85
	v_mul_f32_e32 v106, v41, v85
	v_mul_f32_e32 v107, v25, v85
	s_mov_b64 s[32:33], vcc
	s_nop 0
	s_mov_b64 vcc, s[16:17]
	v_cndmask_b32_dpp v96, v105, v104, vcc quad_perm:[1,0,3,2] row_mask:0xf bank_mask:0xf
	v_cndmask_b32_dpp v97, v107, v106, vcc quad_perm:[1,0,3,2] row_mask:0xf bank_mask:0xf
	s_mov_b64 vcc, s[18:19]
	v_cndmask_b32_dpp v98, v104, v105, vcc quad_perm:[1,0,3,2] row_mask:0xf bank_mask:0xf
	v_cndmask_b32_dpp v107, v106, v107, vcc quad_perm:[1,0,3,2] row_mask:0xf bank_mask:0xf
	s_mov_b64 vcc, s[20:21]
	v_cndmask_b32_dpp v104, v97, v96, vcc quad_perm:[2,3,0,1] row_mask:0xf bank_mask:0xf
	v_cndmask_b32_dpp v105, v107, v98, vcc quad_perm:[2,3,0,1] row_mask:0xf bank_mask:0xf
	s_mov_b64 vcc, s[22:23]
	v_cndmask_b32_dpp v106, v96, v97, vcc quad_perm:[2,3,0,1] row_mask:0xf bank_mask:0xf
	v_cndmask_b32_dpp v107, v98, v107, vcc quad_perm:[2,3,0,1] row_mask:0xf bank_mask:0xf
	s_mov_b64 vcc, s[32:33]
	global_store_dwordx4 v[4:5], v[104:107], off offset:1536
	v_mul_f32_e32 v92, v74, v86
	v_mul_f32_e32 v93, v58, v86
	v_mul_f32_e32 v94, v42, v86
	v_mul_f32_e32 v95, v26, v86
	s_mov_b64 s[32:33], vcc
	s_nop 0
	s_mov_b64 vcc, s[16:17]
	v_cndmask_b32_dpp v96, v93, v92, vcc quad_perm:[1,0,3,2] row_mask:0xf bank_mask:0xf
	v_cndmask_b32_dpp v97, v95, v94, vcc quad_perm:[1,0,3,2] row_mask:0xf bank_mask:0xf
	s_mov_b64 vcc, s[18:19]
	v_cndmask_b32_dpp v98, v92, v93, vcc quad_perm:[1,0,3,2] row_mask:0xf bank_mask:0xf
	v_cndmask_b32_dpp v95, v94, v95, vcc quad_perm:[1,0,3,2] row_mask:0xf bank_mask:0xf
	s_mov_b64 vcc, s[20:21]
	v_cndmask_b32_dpp v92, v97, v96, vcc quad_perm:[2,3,0,1] row_mask:0xf bank_mask:0xf
	v_cndmask_b32_dpp v93, v95, v98, vcc quad_perm:[2,3,0,1] row_mask:0xf bank_mask:0xf
	s_mov_b64 vcc, s[22:23]
	v_cndmask_b32_dpp v94, v96, v97, vcc quad_perm:[2,3,0,1] row_mask:0xf bank_mask:0xf
	v_cndmask_b32_dpp v95, v98, v95, vcc quad_perm:[2,3,0,1] row_mask:0xf bank_mask:0xf
	s_mov_b64 vcc, s[32:33]
	global_store_dwordx4 v[6:7], v[92:95], off
	v_mul_f32_e32 v104, v75, v87
	v_mul_f32_e32 v105, v59, v87
	v_mul_f32_e32 v106, v43, v87
	v_mul_f32_e32 v107, v27, v87
	s_mov_b64 s[32:33], vcc
	s_nop 0
	s_mov_b64 vcc, s[16:17]
	v_cndmask_b32_dpp v96, v105, v104, vcc quad_perm:[1,0,3,2] row_mask:0xf bank_mask:0xf
	v_cndmask_b32_dpp v97, v107, v106, vcc quad_perm:[1,0,3,2] row_mask:0xf bank_mask:0xf
	s_mov_b64 vcc, s[18:19]
	v_cndmask_b32_dpp v98, v104, v105, vcc quad_perm:[1,0,3,2] row_mask:0xf bank_mask:0xf
	v_cndmask_b32_dpp v107, v106, v107, vcc quad_perm:[1,0,3,2] row_mask:0xf bank_mask:0xf
	s_mov_b64 vcc, s[20:21]
	v_cndmask_b32_dpp v104, v97, v96, vcc quad_perm:[2,3,0,1] row_mask:0xf bank_mask:0xf
	v_cndmask_b32_dpp v105, v107, v98, vcc quad_perm:[2,3,0,1] row_mask:0xf bank_mask:0xf
	s_mov_b64 vcc, s[22:23]
	v_cndmask_b32_dpp v106, v96, v97, vcc quad_perm:[2,3,0,1] row_mask:0xf bank_mask:0xf
	v_cndmask_b32_dpp v107, v98, v107, vcc quad_perm:[2,3,0,1] row_mask:0xf bank_mask:0xf
	s_mov_b64 vcc, s[32:33]
	global_store_dwordx4 v[6:7], v[104:107], off offset:512
	v_mul_f32_e32 v92, v76, v88
	v_mul_f32_e32 v93, v60, v88
	v_mul_f32_e32 v94, v44, v88
	v_mul_f32_e32 v95, v28, v88
	s_waitcnt lgkmcnt(0)
; __device__ __forceinline__ int crow(int r,int hi){return (r&3)+8*(r>>2)+4*hi;}
;     ...
;   if constexpr(DV2){ float*Orw=Oraw+(long)wid*QBLK*128;
;     #pragma unroll
;     for(int r=0;r<16;++r){const int orow=crow(r,hi);
;       #pragma unroll
;       for(int d0=0;d0<4;++d0) Orw[orow*128+d0*32+r32]=o[d0][r]*rli[r];}
;     ...
;   asm volatile("s_waitcnt lgkmcnt(0)\n\ts_barrier":::"memory");
	v_rcp_f32_e32 v8, v8
	s_mov_b64 s[32:33], vcc
	s_nop 0
	s_mov_b64 vcc, s[16:17]
	v_cndmask_b32_dpp v96, v93, v92, vcc quad_perm:[1,0,3,2] row_mask:0xf bank_mask:0xf
	v_cndmask_b32_dpp v97, v95, v94, vcc quad_perm:[1,0,3,2] row_mask:0xf bank_mask:0xf
	s_mov_b64 vcc, s[18:19]
	v_cndmask_b32_dpp v98, v92, v93, vcc quad_perm:[1,0,3,2] row_mask:0xf bank_mask:0xf
	v_cndmask_b32_dpp v95, v94, v95, vcc quad_perm:[1,0,3,2] row_mask:0xf bank_mask:0xf
	s_mov_b64 vcc, s[20:21]
	v_cndmask_b32_dpp v92, v97, v96, vcc quad_perm:[2,3,0,1] row_mask:0xf bank_mask:0xf
	v_cndmask_b32_dpp v93, v95, v98, vcc quad_perm:[2,3,0,1] row_mask:0xf bank_mask:0xf
	s_mov_b64 vcc, s[22:23]
	v_cndmask_b32_dpp v94, v96, v97, vcc quad_perm:[2,3,0,1] row_mask:0xf bank_mask:0xf
	v_cndmask_b32_dpp v95, v98, v95, vcc quad_perm:[2,3,0,1] row_mask:0xf bank_mask:0xf
	s_mov_b64 vcc, s[32:33]
	global_store_dwordx4 v[6:7], v[92:95], off offset:1024
	v_mul_f32_e32 v104, v77, v89
	v_mul_f32_e32 v105, v61, v89
	v_mul_f32_e32 v106, v45, v89
	v_mul_f32_e32 v107, v29, v89
	v_add_co_u32_e32 v2, vcc, s89, v2
	v_rcp_f32_e32 v9, v9
	s_mov_b64 s[32:33], vcc
	s_nop 0
	s_mov_b64 vcc, s[16:17]
	v_cndmask_b32_dpp v96, v105, v104, vcc quad_perm:[1,0,3,2] row_mask:0xf bank_mask:0xf
	v_cndmask_b32_dpp v97, v107, v106, vcc quad_perm:[1,0,3,2] row_mask:0xf bank_mask:0xf
	s_mov_b64 vcc, s[18:19]
	v_cndmask_b32_dpp v98, v104, v105, vcc quad_perm:[1,0,3,2] row_mask:0xf bank_mask:0xf
	v_cndmask_b32_dpp v107, v106, v107, vcc quad_perm:[1,0,3,2] row_mask:0xf bank_mask:0xf
	s_mov_b64 vcc, s[20:21]
	v_cndmask_b32_dpp v104, v97, v96, vcc quad_perm:[2,3,0,1] row_mask:0xf bank_mask:0xf
	v_cndmask_b32_dpp v105, v107, v98, vcc quad_perm:[2,3,0,1] row_mask:0xf bank_mask:0xf
	s_mov_b64 vcc, s[22:23]
	v_cndmask_b32_dpp v106, v96, v97, vcc quad_perm:[2,3,0,1] row_mask:0xf bank_mask:0xf
	v_cndmask_b32_dpp v107, v98, v107, vcc quad_perm:[2,3,0,1] row_mask:0xf bank_mask:0xf
	s_mov_b64 vcc, s[32:33]
	global_store_dwordx4 v[6:7], v[104:107], off offset:1536
	v_mul_f32_e32 v92, v78, v8
	v_addc_co_u32_e32 v3, vcc, 0, v3, vcc
	v_mul_f32_e32 v93, v62, v8
	v_mul_f32_e32 v94, v46, v8
	v_mul_f32_e32 v95, v30, v8
	v_rcp_f32_e32 v10, v10
	s_mov_b64 s[32:33], vcc
	s_nop 0
	s_mov_b64 vcc, s[16:17]
	v_cndmask_b32_dpp v96, v93, v92, vcc quad_perm:[1,0,3,2] row_mask:0xf bank_mask:0xf
	v_cndmask_b32_dpp v97, v95, v94, vcc quad_perm:[1,0,3,2] row_mask:0xf bank_mask:0xf
	s_mov_b64 vcc, s[18:19]
	v_cndmask_b32_dpp v98, v92, v93, vcc quad_perm:[1,0,3,2] row_mask:0xf bank_mask:0xf
	v_cndmask_b32_dpp v95, v94, v95, vcc quad_perm:[1,0,3,2] row_mask:0xf bank_mask:0xf
	s_mov_b64 vcc, s[20:21]
	v_cndmask_b32_dpp v92, v97, v96, vcc quad_perm:[2,3,0,1] row_mask:0xf bank_mask:0xf
	v_cndmask_b32_dpp v93, v95, v98, vcc quad_perm:[2,3,0,1] row_mask:0xf bank_mask:0xf
	s_mov_b64 vcc, s[22:23]
	v_cndmask_b32_dpp v94, v96, v97, vcc quad_perm:[2,3,0,1] row_mask:0xf bank_mask:0xf
	v_cndmask_b32_dpp v95, v98, v95, vcc quad_perm:[2,3,0,1] row_mask:0xf bank_mask:0xf
	s_mov_b64 vcc, s[32:33]
	global_store_dwordx4 v[2:3], v[92:95], off
	v_mul_f32_e32 v104, v79, v9
	v_mul_f32_e32 v105, v63, v9
	v_mul_f32_e32 v106, v47, v9
	v_mul_f32_e32 v107, v31, v9
	v_rcp_f32_e32 v11, v11
	s_mov_b64 s[32:33], vcc
	s_nop 0
	s_mov_b64 vcc, s[16:17]
	v_cndmask_b32_dpp v96, v105, v104, vcc quad_perm:[1,0,3,2] row_mask:0xf bank_mask:0xf
	v_cndmask_b32_dpp v97, v107, v106, vcc quad_perm:[1,0,3,2] row_mask:0xf bank_mask:0xf
	s_mov_b64 vcc, s[18:19]
	v_cndmask_b32_dpp v98, v104, v105, vcc quad_perm:[1,0,3,2] row_mask:0xf bank_mask:0xf
	v_cndmask_b32_dpp v107, v106, v107, vcc quad_perm:[1,0,3,2] row_mask:0xf bank_mask:0xf
	s_mov_b64 vcc, s[20:21]
	v_cndmask_b32_dpp v104, v97, v96, vcc quad_perm:[2,3,0,1] row_mask:0xf bank_mask:0xf
	v_cndmask_b32_dpp v105, v107, v98, vcc quad_perm:[2,3,0,1] row_mask:0xf bank_mask:0xf
	s_mov_b64 vcc, s[22:23]
	v_cndmask_b32_dpp v106, v96, v97, vcc quad_perm:[2,3,0,1] row_mask:0xf bank_mask:0xf
	v_cndmask_b32_dpp v107, v98, v107, vcc quad_perm:[2,3,0,1] row_mask:0xf bank_mask:0xf
	s_mov_b64 vcc, s[32:33]
	global_store_dwordx4 v[2:3], v[104:107], off offset:512
	v_mul_f32_e32 v92, v80, v10
	v_mul_f32_e32 v93, v64, v10
	v_mul_f32_e32 v94, v48, v10
	v_mul_f32_e32 v95, v32, v10
	s_mov_b64 s[32:33], vcc
	s_nop 0
	s_mov_b64 vcc, s[16:17]
	v_cndmask_b32_dpp v96, v93, v92, vcc quad_perm:[1,0,3,2] row_mask:0xf bank_mask:0xf
	v_cndmask_b32_dpp v97, v95, v94, vcc quad_perm:[1,0,3,2] row_mask:0xf bank_mask:0xf
	s_mov_b64 vcc, s[18:19]
	v_cndmask_b32_dpp v98, v92, v93, vcc quad_perm:[1,0,3,2] row_mask:0xf bank_mask:0xf
	v_cndmask_b32_dpp v95, v94, v95, vcc quad_perm:[1,0,3,2] row_mask:0xf bank_mask:0xf
	s_mov_b64 vcc, s[20:21]
	v_cndmask_b32_dpp v92, v97, v96, vcc quad_perm:[2,3,0,1] row_mask:0xf bank_mask:0xf
	v_cndmask_b32_dpp v93, v95, v98, vcc quad_perm:[2,3,0,1] row_mask:0xf bank_mask:0xf
	s_mov_b64 vcc, s[22:23]
	v_cndmask_b32_dpp v94, v96, v97, vcc quad_perm:[2,3,0,1] row_mask:0xf bank_mask:0xf
	v_cndmask_b32_dpp v95, v98, v95, vcc quad_perm:[2,3,0,1] row_mask:0xf bank_mask:0xf
	s_mov_b64 vcc, s[32:33]
	global_store_dwordx4 v[2:3], v[92:95], off offset:1024
	v_mul_f32_e32 v104, v81, v11
	v_mul_f32_e32 v105, v65, v11
	v_mul_f32_e32 v106, v49, v11
	v_mul_f32_e32 v107, v33, v11
	s_mov_b64 s[32:33], vcc
	s_nop 0
	s_mov_b64 vcc, s[16:17]
	v_cndmask_b32_dpp v96, v105, v104, vcc quad_perm:[1,0,3,2] row_mask:0xf bank_mask:0xf
	v_cndmask_b32_dpp v97, v107, v106, vcc quad_perm:[1,0,3,2] row_mask:0xf bank_mask:0xf
	s_mov_b64 vcc, s[18:19]
	v_cndmask_b32_dpp v98, v104, v105, vcc quad_perm:[1,0,3,2] row_mask:0xf bank_mask:0xf
	v_cndmask_b32_dpp v107, v106, v107, vcc quad_perm:[1,0,3,2] row_mask:0xf bank_mask:0xf
	s_mov_b64 vcc, s[20:21]
	v_cndmask_b32_dpp v104, v97, v96, vcc quad_perm:[2,3,0,1] row_mask:0xf bank_mask:0xf
	v_cndmask_b32_dpp v105, v107, v98, vcc quad_perm:[2,3,0,1] row_mask:0xf bank_mask:0xf
	s_mov_b64 vcc, s[22:23]
	v_cndmask_b32_dpp v106, v96, v97, vcc quad_perm:[2,3,0,1] row_mask:0xf bank_mask:0xf
	v_cndmask_b32_dpp v107, v98, v107, vcc quad_perm:[2,3,0,1] row_mask:0xf bank_mask:0xf
	s_mov_b64 vcc, s[32:33]
	global_store_dwordx4 v[2:3], v[104:107], off offset:1536
	s_waitcnt lgkmcnt(0)
	s_barrier
	s_mov_b32 s42, 1
	s_mov_b64 s[8:9], 0
	s_and_b64 vcc, exec, s[14:15]
	s_cbranch_vccnz .LBB0_330
